# ffn_in: 4x1 wave layout (each wave owns 32 rows of both A tiles, private LDS rows refilled without the mid-step barrier; all 128 B columns per wave)
# speedup vs baseline: 1.0014x; 1.0014x over previous
.Lf2_setup:
	v_and_b32_e32 v70, 7, v196
	v_bfe_u32 v71, v196, 4, 2
	v_bfe_u32 v72, v196, 6, 1
	v_lshl_or_b32 v73, v72, 2, v71
	v_xor_b32_e32 v82, v70, v73
	v_lshrrev_b32_e32 v73, 3, v196
	v_lshlrev_b32_e32 v73, 11, v73
	v_lshl_or_b32 v76, v82, 4, v73
	v_xor_b32_e32 v82, v70, v71
	v_bfe_u32 v73, v196, 3, 3
	v_lshrrev_b32_e32 v83, 6, v196
	v_lshl_or_b32 v73, v83, 5, v73
	v_lshlrev_b32_e32 v73, 11, v73
	v_lshl_or_b32 v77, v82, 4, v73
	v_xor_b32_e32 v78, 64, v77
	v_and_b32_e32 v70, 15, v196
	v_bfe_u32 v73, v196, 1, 3
	v_xor_b32_e32 v73, v71, v73
	v_lshlrev_b32_e32 v73, 4, v73
	v_xor_b32_e32 v82, 64, v73
	v_lshlrev_b32_e32 v70, 7, v70
	v_lshl_or_b32 v83, v83, 12, v70
	v_add_u32_e32 v80, v83, v73
	v_add_u32_e32 v81, v83, v82
	v_add_u32_e32 v144, v70, v73
	v_add_u32_e32 v145, v70, v82
	v_readfirstlane_b32 s64, v196
	s_lshr_b32 s64, s64, 6
	s_lshl_b32 s64, s64, 10
	s_cmp_eq_u32 s39, 2
	s_cbranch_scc1 .Lf2_loop
	s_lshl_b32 s30, s8, 18
	s_add_u32 s50, s6, s30
	s_addc_u32 s51, s7, 0
	s_lshl_b32 s30, s49, 18
	s_add_u32 s52, s6, s30
	s_addc_u32 s53, s7, 0
	s_lshl_b32 s30, s21, 18
	s_add_u32 s58, s19, s30
	s_addc_u32 s59, s20, 0
	s_barrier
	s_lshl_b32 m0, s64, 2
	s_add_i32 m0, m0, 0x0
	s_nop 0
	global_load_lds_dwordx4 v77, s[50:51]
	s_add_u32 s50, s50, 0x4000
	s_addc_u32 s51, s51, 0
	s_lshl_b32 m0, s64, 2
	s_add_i32 m0, m0, 0x400
	s_nop 0
	global_load_lds_dwordx4 v78, s[50:51]
	s_add_u32 s50, s50, 0x4000
	s_addc_u32 s51, s51, 0
	s_lshl_b32 m0, s64, 2
	s_add_i32 m0, m0, 0x800
	s_nop 0
	global_load_lds_dwordx4 v77, s[50:51]
	s_add_u32 s50, s50, 0x4000
	s_addc_u32 s51, s51, 0
	s_lshl_b32 m0, s64, 2
	s_add_i32 m0, m0, 0xc00
	s_nop 0
	global_load_lds_dwordx4 v78, s[50:51]
	s_sub_u32 s50, s50, 0xbf80
	s_subb_u32 s51, s51, 0
	s_lshl_b32 m0, s64, 2
	s_add_i32 m0, m0, 0x4000
	s_nop 0
	global_load_lds_dwordx4 v77, s[52:53]
	s_add_u32 s52, s52, 0x4000
	s_addc_u32 s53, s53, 0
	s_lshl_b32 m0, s64, 2
	s_add_i32 m0, m0, 0x4400
	s_nop 0
	global_load_lds_dwordx4 v78, s[52:53]
	s_add_u32 s52, s52, 0x4000
	s_addc_u32 s53, s53, 0
	s_lshl_b32 m0, s64, 2
	s_add_i32 m0, m0, 0x4800
	s_nop 0
	global_load_lds_dwordx4 v77, s[52:53]
	s_add_u32 s52, s52, 0x4000
	s_addc_u32 s53, s53, 0
	s_lshl_b32 m0, s64, 2
	s_add_i32 m0, m0, 0x4c00
	s_nop 0
	global_load_lds_dwordx4 v78, s[52:53]
	s_sub_u32 s52, s52, 0xbf80
	s_subb_u32 s53, s53, 0
	s_add_i32 m0, s64, 0x8000
	s_nop 0
	global_load_lds_dwordx4 v76, s[58:59]
	s_add_u32 s58, s58, 0x10000
	s_addc_u32 s59, s59, 0
	s_add_i32 m0, s64, 0x9000
	s_nop 0
	global_load_lds_dwordx4 v76, s[58:59]
	s_add_u32 s58, s58, 0x10000
	s_addc_u32 s59, s59, 0
	s_add_i32 m0, s64, 0xa000
	s_nop 0
	global_load_lds_dwordx4 v76, s[58:59]
	s_add_u32 s58, s58, 0x10000
	s_addc_u32 s59, s59, 0
	s_add_i32 m0, s64, 0xb000
	s_nop 0
	global_load_lds_dwordx4 v76, s[58:59]
	s_sub_u32 s58, s58, 0x2ff80
	s_subb_u32 s59, s59, 0

.Lf2_k:
	s_waitcnt vmcnt(0)
	s_barrier
	s_add_i32 m0, s64, 0xc000
	s_nop 0
	global_load_lds_dwordx4 v76, s[58:59]
	s_add_u32 s58, s58, 0x10000
	s_addc_u32 s59, s59, 0
	s_add_i32 m0, s64, 0xd000
	s_nop 0
	global_load_lds_dwordx4 v76, s[58:59]
	s_add_u32 s58, s58, 0x10000
	s_addc_u32 s59, s59, 0
	s_add_i32 m0, s64, 0xe000
	s_nop 0
	global_load_lds_dwordx4 v76, s[58:59]
	s_add_u32 s58, s58, 0x10000
	s_addc_u32 s59, s59, 0
	s_add_i32 m0, s64, 0xf000
	s_nop 0
	global_load_lds_dwordx4 v76, s[58:59]
	s_sub_u32 s58, s58, 0x2ff80
	s_subb_u32 s59, s59, 0
	ds_read_b128 v[148:151], v80 offset:0
	ds_read_b128 v[152:155], v80 offset:2048
	ds_read_b128 v[164:167], v144 offset:32768
	ds_read_b128 v[168:171], v144 offset:34816
	ds_read_b128 v[174:177], v144 offset:36864
	ds_read_b128 v[182:185], v144 offset:38912
	ds_read_b128 v[188:191], v144 offset:40960
	ds_read_b128 v[192:195], v144 offset:43008
	ds_read_b128 v[208:211], v144 offset:45056
	ds_read_b128 v[212:215], v144 offset:47104
	ds_read_b128 v[156:159], v80 offset:16384
	ds_read_b128 v[160:163], v80 offset:18432
	s_setprio 1
	s_waitcnt lgkmcnt(2)
	v_mfma_f32_16x16x32_bf16 v[62:65], v[164:167], v[148:151], v[62:65]
	v_mfma_f32_16x16x32_bf16 v[54:57], v[168:171], v[148:151], v[54:57]
	v_mfma_f32_16x16x32_bf16 v[58:61], v[174:177], v[148:151], v[58:61]
	v_mfma_f32_16x16x32_bf16 v[50:53], v[182:185], v[148:151], v[50:53]
	v_mfma_f32_16x16x32_bf16 v[46:49], v[188:191], v[148:151], v[46:49]
	v_mfma_f32_16x16x32_bf16 v[38:41], v[192:195], v[148:151], v[38:41]
	v_mfma_f32_16x16x32_bf16 v[42:45], v[208:211], v[148:151], v[42:45]
	v_mfma_f32_16x16x32_bf16 v[34:37], v[212:215], v[148:151], v[34:37]
	v_mfma_f32_16x16x32_bf16 v[30:33], v[164:167], v[152:155], v[30:33]
	v_mfma_f32_16x16x32_bf16 v[22:25], v[168:171], v[152:155], v[22:25]
	v_mfma_f32_16x16x32_bf16 v[26:29], v[174:177], v[152:155], v[26:29]
	v_mfma_f32_16x16x32_bf16 v[18:21], v[182:185], v[152:155], v[18:21]
	v_mfma_f32_16x16x32_bf16 v[14:17], v[188:191], v[152:155], v[14:17]
	v_mfma_f32_16x16x32_bf16 v[6:9], v[192:195], v[152:155], v[6:9]
	v_mfma_f32_16x16x32_bf16 v[10:13], v[208:211], v[152:155], v[10:13]
	v_mfma_f32_16x16x32_bf16 v[2:5], v[212:215], v[152:155], v[2:5]
	s_waitcnt lgkmcnt(0)
	v_mfma_f32_16x16x32_bf16 v[66:69], v[164:167], v[156:159], v[66:69]
	v_mfma_f32_16x16x32_bf16 v[70:73], v[168:171], v[156:159], v[70:73]
	v_mfma_f32_16x16x32_bf16 v[82:85], v[174:177], v[156:159], v[82:85]
	v_mfma_f32_16x16x32_bf16 v[86:89], v[182:185], v[156:159], v[86:89]
	v_mfma_f32_16x16x32_bf16 v[90:93], v[188:191], v[156:159], v[90:93]
	v_mfma_f32_16x16x32_bf16 v[94:97], v[192:195], v[156:159], v[94:97]
	v_mfma_f32_16x16x32_bf16 v[98:101], v[208:211], v[156:159], v[98:101]
	v_mfma_f32_16x16x32_bf16 v[102:105], v[212:215], v[156:159], v[102:105]
	v_mfma_f32_16x16x32_bf16 v[106:109], v[164:167], v[160:163], v[106:109]
	v_mfma_f32_16x16x32_bf16 v[110:113], v[168:171], v[160:163], v[110:113]
	v_mfma_f32_16x16x32_bf16 v[114:117], v[174:177], v[160:163], v[114:117]
	v_mfma_f32_16x16x32_bf16 v[118:121], v[182:185], v[160:163], v[118:121]
	v_mfma_f32_16x16x32_bf16 v[122:125], v[188:191], v[160:163], v[122:125]
	v_mfma_f32_16x16x32_bf16 v[126:129], v[192:195], v[160:163], v[126:129]
	v_mfma_f32_16x16x32_bf16 v[136:139], v[208:211], v[160:163], v[136:139]
	v_mfma_f32_16x16x32_bf16 v[140:143], v[212:215], v[160:163], v[140:143]
	s_setprio 0
	ds_read_b128 v[148:151], v81 offset:0
	ds_read_b128 v[152:155], v81 offset:2048
	ds_read_b128 v[164:167], v145 offset:32768
	ds_read_b128 v[168:171], v145 offset:34816
	ds_read_b128 v[174:177], v145 offset:36864
	ds_read_b128 v[182:185], v145 offset:38912
	ds_read_b128 v[188:191], v145 offset:40960
	ds_read_b128 v[192:195], v145 offset:43008
	ds_read_b128 v[208:211], v145 offset:45056
	ds_read_b128 v[212:215], v145 offset:47104
	ds_read_b128 v[156:159], v81 offset:16384
	ds_read_b128 v[160:163], v81 offset:18432
	s_waitcnt lgkmcnt(0)
	s_lshl_b32 m0, s64, 2
	s_add_i32 m0, m0, 0x0
	s_nop 0
	global_load_lds_dwordx4 v77, s[50:51]
	s_add_u32 s50, s50, 0x4000
	s_addc_u32 s51, s51, 0
	s_lshl_b32 m0, s64, 2
	s_add_i32 m0, m0, 0x400
	s_nop 0
	global_load_lds_dwordx4 v78, s[50:51]
	s_add_u32 s50, s50, 0x4000
	s_addc_u32 s51, s51, 0
	s_lshl_b32 m0, s64, 2
	s_add_i32 m0, m0, 0x800
	s_nop 0
	global_load_lds_dwordx4 v77, s[50:51]
	s_add_u32 s50, s50, 0x4000
	s_addc_u32 s51, s51, 0
	s_lshl_b32 m0, s64, 2
	s_add_i32 m0, m0, 0xc00
	s_nop 0
	global_load_lds_dwordx4 v78, s[50:51]
	s_sub_u32 s50, s50, 0xbf80
	s_subb_u32 s51, s51, 0
	s_lshl_b32 m0, s64, 2
	s_add_i32 m0, m0, 0x4000
	s_nop 0
	global_load_lds_dwordx4 v77, s[52:53]
	s_add_u32 s52, s52, 0x4000
	s_addc_u32 s53, s53, 0
	s_lshl_b32 m0, s64, 2
	s_add_i32 m0, m0, 0x4400
	s_nop 0
	global_load_lds_dwordx4 v78, s[52:53]
	s_add_u32 s52, s52, 0x4000
	s_addc_u32 s53, s53, 0
	s_lshl_b32 m0, s64, 2
	s_add_i32 m0, m0, 0x4800
	s_nop 0
	global_load_lds_dwordx4 v77, s[52:53]
	s_add_u32 s52, s52, 0x4000
	s_addc_u32 s53, s53, 0
	s_lshl_b32 m0, s64, 2
	s_add_i32 m0, m0, 0x4c00
	s_nop 0
	global_load_lds_dwordx4 v78, s[52:53]
	s_sub_u32 s52, s52, 0xbf80
	s_subb_u32 s53, s53, 0
	s_setprio 1
	v_mfma_f32_16x16x32_bf16 v[62:65], v[164:167], v[148:151], v[62:65]
	v_mfma_f32_16x16x32_bf16 v[54:57], v[168:171], v[148:151], v[54:57]
	v_mfma_f32_16x16x32_bf16 v[58:61], v[174:177], v[148:151], v[58:61]
	v_mfma_f32_16x16x32_bf16 v[50:53], v[182:185], v[148:151], v[50:53]
	v_mfma_f32_16x16x32_bf16 v[46:49], v[188:191], v[148:151], v[46:49]
	v_mfma_f32_16x16x32_bf16 v[38:41], v[192:195], v[148:151], v[38:41]
	v_mfma_f32_16x16x32_bf16 v[42:45], v[208:211], v[148:151], v[42:45]
	v_mfma_f32_16x16x32_bf16 v[34:37], v[212:215], v[148:151], v[34:37]
	v_mfma_f32_16x16x32_bf16 v[30:33], v[164:167], v[152:155], v[30:33]
	v_mfma_f32_16x16x32_bf16 v[22:25], v[168:171], v[152:155], v[22:25]
	v_mfma_f32_16x16x32_bf16 v[26:29], v[174:177], v[152:155], v[26:29]
	v_mfma_f32_16x16x32_bf16 v[18:21], v[182:185], v[152:155], v[18:21]
	v_mfma_f32_16x16x32_bf16 v[14:17], v[188:191], v[152:155], v[14:17]
	v_mfma_f32_16x16x32_bf16 v[6:9], v[192:195], v[152:155], v[6:9]
	v_mfma_f32_16x16x32_bf16 v[10:13], v[208:211], v[152:155], v[10:13]
	v_mfma_f32_16x16x32_bf16 v[2:5], v[212:215], v[152:155], v[2:5]
	s_waitcnt lgkmcnt(0)
	v_mfma_f32_16x16x32_bf16 v[66:69], v[164:167], v[156:159], v[66:69]
	v_mfma_f32_16x16x32_bf16 v[70:73], v[168:171], v[156:159], v[70:73]
	v_mfma_f32_16x16x32_bf16 v[82:85], v[174:177], v[156:159], v[82:85]
	v_mfma_f32_16x16x32_bf16 v[86:89], v[182:185], v[156:159], v[86:89]
	v_mfma_f32_16x16x32_bf16 v[90:93], v[188:191], v[156:159], v[90:93]
	v_mfma_f32_16x16x32_bf16 v[94:97], v[192:195], v[156:159], v[94:97]
	v_mfma_f32_16x16x32_bf16 v[98:101], v[208:211], v[156:159], v[98:101]
	v_mfma_f32_16x16x32_bf16 v[102:105], v[212:215], v[156:159], v[102:105]
	v_mfma_f32_16x16x32_bf16 v[106:109], v[164:167], v[160:163], v[106:109]
	v_mfma_f32_16x16x32_bf16 v[110:113], v[168:171], v[160:163], v[110:113]
	v_mfma_f32_16x16x32_bf16 v[114:117], v[174:177], v[160:163], v[114:117]
	v_mfma_f32_16x16x32_bf16 v[118:121], v[182:185], v[160:163], v[118:121]
	v_mfma_f32_16x16x32_bf16 v[122:125], v[188:191], v[160:163], v[122:125]
	v_mfma_f32_16x16x32_bf16 v[126:129], v[192:195], v[160:163], v[126:129]
	v_mfma_f32_16x16x32_bf16 v[136:139], v[208:211], v[160:163], v[136:139]
	v_mfma_f32_16x16x32_bf16 v[140:143], v[212:215], v[160:163], v[140:143]
	s_setprio 0
	s_waitcnt vmcnt(0)
	s_barrier
	s_add_i32 m0, s64, 0x8000
	s_nop 0
	global_load_lds_dwordx4 v76, s[58:59]
	s_add_u32 s58, s58, 0x10000
	s_addc_u32 s59, s59, 0
	s_add_i32 m0, s64, 0x9000
	s_nop 0
	global_load_lds_dwordx4 v76, s[58:59]
	s_add_u32 s58, s58, 0x10000
	s_addc_u32 s59, s59, 0
	s_add_i32 m0, s64, 0xa000
	s_nop 0
	global_load_lds_dwordx4 v76, s[58:59]
	s_add_u32 s58, s58, 0x10000
	s_addc_u32 s59, s59, 0
	s_add_i32 m0, s64, 0xb000
	s_nop 0
	global_load_lds_dwordx4 v76, s[58:59]
	s_sub_u32 s58, s58, 0x2ff80
	s_subb_u32 s59, s59, 0
	ds_read_b128 v[148:151], v80 offset:0
	ds_read_b128 v[152:155], v80 offset:2048
	ds_read_b128 v[164:167], v144 offset:49152
	ds_read_b128 v[168:171], v144 offset:51200
	ds_read_b128 v[174:177], v144 offset:53248
	ds_read_b128 v[182:185], v144 offset:55296
	ds_read_b128 v[188:191], v144 offset:57344
	ds_read_b128 v[192:195], v144 offset:59392
	ds_read_b128 v[208:211], v144 offset:61440
	ds_read_b128 v[212:215], v144 offset:63488
	ds_read_b128 v[156:159], v80 offset:16384
	ds_read_b128 v[160:163], v80 offset:18432
	s_setprio 1
	s_waitcnt lgkmcnt(2)
	v_mfma_f32_16x16x32_bf16 v[62:65], v[164:167], v[148:151], v[62:65]
	v_mfma_f32_16x16x32_bf16 v[54:57], v[168:171], v[148:151], v[54:57]
	v_mfma_f32_16x16x32_bf16 v[58:61], v[174:177], v[148:151], v[58:61]
	v_mfma_f32_16x16x32_bf16 v[50:53], v[182:185], v[148:151], v[50:53]
	v_mfma_f32_16x16x32_bf16 v[46:49], v[188:191], v[148:151], v[46:49]
	v_mfma_f32_16x16x32_bf16 v[38:41], v[192:195], v[148:151], v[38:41]
	v_mfma_f32_16x16x32_bf16 v[42:45], v[208:211], v[148:151], v[42:45]
	v_mfma_f32_16x16x32_bf16 v[34:37], v[212:215], v[148:151], v[34:37]
	v_mfma_f32_16x16x32_bf16 v[30:33], v[164:167], v[152:155], v[30:33]
	v_mfma_f32_16x16x32_bf16 v[22:25], v[168:171], v[152:155], v[22:25]
	v_mfma_f32_16x16x32_bf16 v[26:29], v[174:177], v[152:155], v[26:29]
	v_mfma_f32_16x16x32_bf16 v[18:21], v[182:185], v[152:155], v[18:21]
	v_mfma_f32_16x16x32_bf16 v[14:17], v[188:191], v[152:155], v[14:17]
	v_mfma_f32_16x16x32_bf16 v[6:9], v[192:195], v[152:155], v[6:9]
	v_mfma_f32_16x16x32_bf16 v[10:13], v[208:211], v[152:155], v[10:13]
	v_mfma_f32_16x16x32_bf16 v[2:5], v[212:215], v[152:155], v[2:5]
	s_waitcnt lgkmcnt(0)
	v_mfma_f32_16x16x32_bf16 v[66:69], v[164:167], v[156:159], v[66:69]
	v_mfma_f32_16x16x32_bf16 v[70:73], v[168:171], v[156:159], v[70:73]
	v_mfma_f32_16x16x32_bf16 v[82:85], v[174:177], v[156:159], v[82:85]
	v_mfma_f32_16x16x32_bf16 v[86:89], v[182:185], v[156:159], v[86:89]
	v_mfma_f32_16x16x32_bf16 v[90:93], v[188:191], v[156:159], v[90:93]
	v_mfma_f32_16x16x32_bf16 v[94:97], v[192:195], v[156:159], v[94:97]
	v_mfma_f32_16x16x32_bf16 v[98:101], v[208:211], v[156:159], v[98:101]
	v_mfma_f32_16x16x32_bf16 v[102:105], v[212:215], v[156:159], v[102:105]
	v_mfma_f32_16x16x32_bf16 v[106:109], v[164:167], v[160:163], v[106:109]
	v_mfma_f32_16x16x32_bf16 v[110:113], v[168:171], v[160:163], v[110:113]
	v_mfma_f32_16x16x32_bf16 v[114:117], v[174:177], v[160:163], v[114:117]
	v_mfma_f32_16x16x32_bf16 v[118:121], v[182:185], v[160:163], v[118:121]
	v_mfma_f32_16x16x32_bf16 v[122:125], v[188:191], v[160:163], v[122:125]
	v_mfma_f32_16x16x32_bf16 v[126:129], v[192:195], v[160:163], v[126:129]
	v_mfma_f32_16x16x32_bf16 v[136:139], v[208:211], v[160:163], v[136:139]
	v_mfma_f32_16x16x32_bf16 v[140:143], v[212:215], v[160:163], v[140:143]
	s_setprio 0
	ds_read_b128 v[148:151], v81 offset:0
	ds_read_b128 v[152:155], v81 offset:2048
	ds_read_b128 v[164:167], v145 offset:49152
	ds_read_b128 v[168:171], v145 offset:51200
	ds_read_b128 v[174:177], v145 offset:53248
	ds_read_b128 v[182:185], v145 offset:55296
	ds_read_b128 v[188:191], v145 offset:57344
	ds_read_b128 v[192:195], v145 offset:59392
	ds_read_b128 v[208:211], v145 offset:61440
	ds_read_b128 v[212:215], v145 offset:63488
	ds_read_b128 v[156:159], v81 offset:16384
	ds_read_b128 v[160:163], v81 offset:18432
	s_waitcnt lgkmcnt(0)
	s_lshl_b32 m0, s64, 2
	s_add_i32 m0, m0, 0x0
	s_nop 0
	global_load_lds_dwordx4 v77, s[50:51]
	s_add_u32 s50, s50, 0x4000
	s_addc_u32 s51, s51, 0
	s_lshl_b32 m0, s64, 2
	s_add_i32 m0, m0, 0x400
	s_nop 0
	global_load_lds_dwordx4 v78, s[50:51]
	s_add_u32 s50, s50, 0x4000
	s_addc_u32 s51, s51, 0
	s_lshl_b32 m0, s64, 2
	s_add_i32 m0, m0, 0x800
	s_nop 0
	global_load_lds_dwordx4 v77, s[50:51]
	s_add_u32 s50, s50, 0x4000
	s_addc_u32 s51, s51, 0
	s_lshl_b32 m0, s64, 2
	s_add_i32 m0, m0, 0xc00
	s_nop 0
	global_load_lds_dwordx4 v78, s[50:51]
	s_sub_u32 s50, s50, 0xbf80
	s_subb_u32 s51, s51, 0
	s_lshl_b32 m0, s64, 2
	s_add_i32 m0, m0, 0x4000
	s_nop 0
	global_load_lds_dwordx4 v77, s[52:53]
	s_add_u32 s52, s52, 0x4000
	s_addc_u32 s53, s53, 0
	s_lshl_b32 m0, s64, 2
	s_add_i32 m0, m0, 0x4400
	s_nop 0
	global_load_lds_dwordx4 v78, s[52:53]
	s_add_u32 s52, s52, 0x4000
	s_addc_u32 s53, s53, 0
	s_lshl_b32 m0, s64, 2
	s_add_i32 m0, m0, 0x4800
	s_nop 0
	global_load_lds_dwordx4 v77, s[52:53]
	s_add_u32 s52, s52, 0x4000
	s_addc_u32 s53, s53, 0
	s_lshl_b32 m0, s64, 2
	s_add_i32 m0, m0, 0x4c00
	s_nop 0
	global_load_lds_dwordx4 v78, s[52:53]
	s_sub_u32 s52, s52, 0xbf80
	s_subb_u32 s53, s53, 0
	s_setprio 1
	v_mfma_f32_16x16x32_bf16 v[62:65], v[164:167], v[148:151], v[62:65]
	v_mfma_f32_16x16x32_bf16 v[54:57], v[168:171], v[148:151], v[54:57]
	v_mfma_f32_16x16x32_bf16 v[58:61], v[174:177], v[148:151], v[58:61]
	v_mfma_f32_16x16x32_bf16 v[50:53], v[182:185], v[148:151], v[50:53]
	v_mfma_f32_16x16x32_bf16 v[46:49], v[188:191], v[148:151], v[46:49]
	v_mfma_f32_16x16x32_bf16 v[38:41], v[192:195], v[148:151], v[38:41]
	v_mfma_f32_16x16x32_bf16 v[42:45], v[208:211], v[148:151], v[42:45]
	v_mfma_f32_16x16x32_bf16 v[34:37], v[212:215], v[148:151], v[34:37]
	v_mfma_f32_16x16x32_bf16 v[30:33], v[164:167], v[152:155], v[30:33]
	v_mfma_f32_16x16x32_bf16 v[22:25], v[168:171], v[152:155], v[22:25]
	v_mfma_f32_16x16x32_bf16 v[26:29], v[174:177], v[152:155], v[26:29]
	v_mfma_f32_16x16x32_bf16 v[18:21], v[182:185], v[152:155], v[18:21]
	v_mfma_f32_16x16x32_bf16 v[14:17], v[188:191], v[152:155], v[14:17]
	v_mfma_f32_16x16x32_bf16 v[6:9], v[192:195], v[152:155], v[6:9]
	v_mfma_f32_16x16x32_bf16 v[10:13], v[208:211], v[152:155], v[10:13]
	v_mfma_f32_16x16x32_bf16 v[2:5], v[212:215], v[152:155], v[2:5]
	s_waitcnt lgkmcnt(0)
	v_mfma_f32_16x16x32_bf16 v[66:69], v[164:167], v[156:159], v[66:69]
	v_mfma_f32_16x16x32_bf16 v[70:73], v[168:171], v[156:159], v[70:73]
	v_mfma_f32_16x16x32_bf16 v[82:85], v[174:177], v[156:159], v[82:85]
	v_mfma_f32_16x16x32_bf16 v[86:89], v[182:185], v[156:159], v[86:89]
	v_mfma_f32_16x16x32_bf16 v[90:93], v[188:191], v[156:159], v[90:93]
	v_mfma_f32_16x16x32_bf16 v[94:97], v[192:195], v[156:159], v[94:97]
	v_mfma_f32_16x16x32_bf16 v[98:101], v[208:211], v[156:159], v[98:101]
	v_mfma_f32_16x16x32_bf16 v[102:105], v[212:215], v[156:159], v[102:105]
	v_mfma_f32_16x16x32_bf16 v[106:109], v[164:167], v[160:163], v[106:109]
	v_mfma_f32_16x16x32_bf16 v[110:113], v[168:171], v[160:163], v[110:113]
	v_mfma_f32_16x16x32_bf16 v[114:117], v[174:177], v[160:163], v[114:117]
	v_mfma_f32_16x16x32_bf16 v[118:121], v[182:185], v[160:163], v[118:121]
	v_mfma_f32_16x16x32_bf16 v[122:125], v[188:191], v[160:163], v[122:125]
	v_mfma_f32_16x16x32_bf16 v[126:129], v[192:195], v[160:163], v[126:129]
	v_mfma_f32_16x16x32_bf16 v[136:139], v[208:211], v[160:163], v[136:139]
	v_mfma_f32_16x16x32_bf16 v[140:143], v[212:215], v[160:163], v[140:143]
	s_setprio 0
	s_add_i32 s65, s65, -1
	s_cmp_lg_u32 s65, 0
	s_cbranch_scc1 .Lf2_k
	s_waitcnt vmcnt(0)
	s_barrier
	s_add_i32 m0, s64, 0xc000
	s_nop 0
	global_load_lds_dwordx4 v76, s[58:59]
	s_add_u32 s58, s58, 0x10000
	s_addc_u32 s59, s59, 0
	s_add_i32 m0, s64, 0xd000
	s_nop 0
	global_load_lds_dwordx4 v76, s[58:59]
	s_add_u32 s58, s58, 0x10000
	s_addc_u32 s59, s59, 0
	s_add_i32 m0, s64, 0xe000
	s_nop 0
	global_load_lds_dwordx4 v76, s[58:59]
	s_add_u32 s58, s58, 0x10000
	s_addc_u32 s59, s59, 0
	s_add_i32 m0, s64, 0xf000
	s_nop 0
	global_load_lds_dwordx4 v76, s[58:59]
	s_sub_u32 s58, s58, 0x2ff80
	s_subb_u32 s59, s59, 0
	ds_read_b128 v[148:151], v80 offset:0
	ds_read_b128 v[152:155], v80 offset:2048
	ds_read_b128 v[164:167], v144 offset:32768
	ds_read_b128 v[168:171], v144 offset:34816
	ds_read_b128 v[174:177], v144 offset:36864
	ds_read_b128 v[182:185], v144 offset:38912
	ds_read_b128 v[188:191], v144 offset:40960
	ds_read_b128 v[192:195], v144 offset:43008
	ds_read_b128 v[208:211], v144 offset:45056
	ds_read_b128 v[212:215], v144 offset:47104
	ds_read_b128 v[156:159], v80 offset:16384
	ds_read_b128 v[160:163], v80 offset:18432
	s_setprio 1
	s_waitcnt lgkmcnt(2)
	v_mfma_f32_16x16x32_bf16 v[62:65], v[164:167], v[148:151], v[62:65]
	v_mfma_f32_16x16x32_bf16 v[54:57], v[168:171], v[148:151], v[54:57]
	v_mfma_f32_16x16x32_bf16 v[58:61], v[174:177], v[148:151], v[58:61]
	v_mfma_f32_16x16x32_bf16 v[50:53], v[182:185], v[148:151], v[50:53]
	v_mfma_f32_16x16x32_bf16 v[46:49], v[188:191], v[148:151], v[46:49]
	v_mfma_f32_16x16x32_bf16 v[38:41], v[192:195], v[148:151], v[38:41]
	v_mfma_f32_16x16x32_bf16 v[42:45], v[208:211], v[148:151], v[42:45]
	v_mfma_f32_16x16x32_bf16 v[34:37], v[212:215], v[148:151], v[34:37]
	v_mfma_f32_16x16x32_bf16 v[30:33], v[164:167], v[152:155], v[30:33]
	v_mfma_f32_16x16x32_bf16 v[22:25], v[168:171], v[152:155], v[22:25]
	v_mfma_f32_16x16x32_bf16 v[26:29], v[174:177], v[152:155], v[26:29]
	v_mfma_f32_16x16x32_bf16 v[18:21], v[182:185], v[152:155], v[18:21]
	v_mfma_f32_16x16x32_bf16 v[14:17], v[188:191], v[152:155], v[14:17]
	v_mfma_f32_16x16x32_bf16 v[6:9], v[192:195], v[152:155], v[6:9]
	v_mfma_f32_16x16x32_bf16 v[10:13], v[208:211], v[152:155], v[10:13]
	v_mfma_f32_16x16x32_bf16 v[2:5], v[212:215], v[152:155], v[2:5]
	s_waitcnt lgkmcnt(0)
	v_mfma_f32_16x16x32_bf16 v[66:69], v[164:167], v[156:159], v[66:69]
	v_mfma_f32_16x16x32_bf16 v[70:73], v[168:171], v[156:159], v[70:73]
	v_mfma_f32_16x16x32_bf16 v[82:85], v[174:177], v[156:159], v[82:85]
	v_mfma_f32_16x16x32_bf16 v[86:89], v[182:185], v[156:159], v[86:89]
	v_mfma_f32_16x16x32_bf16 v[90:93], v[188:191], v[156:159], v[90:93]
	v_mfma_f32_16x16x32_bf16 v[94:97], v[192:195], v[156:159], v[94:97]
	v_mfma_f32_16x16x32_bf16 v[98:101], v[208:211], v[156:159], v[98:101]
	v_mfma_f32_16x16x32_bf16 v[102:105], v[212:215], v[156:159], v[102:105]
	v_mfma_f32_16x16x32_bf16 v[106:109], v[164:167], v[160:163], v[106:109]
	v_mfma_f32_16x16x32_bf16 v[110:113], v[168:171], v[160:163], v[110:113]
	v_mfma_f32_16x16x32_bf16 v[114:117], v[174:177], v[160:163], v[114:117]
	v_mfma_f32_16x16x32_bf16 v[118:121], v[182:185], v[160:163], v[118:121]
	v_mfma_f32_16x16x32_bf16 v[122:125], v[188:191], v[160:163], v[122:125]
	v_mfma_f32_16x16x32_bf16 v[126:129], v[192:195], v[160:163], v[126:129]
	v_mfma_f32_16x16x32_bf16 v[136:139], v[208:211], v[160:163], v[136:139]
	v_mfma_f32_16x16x32_bf16 v[140:143], v[212:215], v[160:163], v[140:143]
	s_setprio 0
	ds_read_b128 v[148:151], v81 offset:0
	ds_read_b128 v[152:155], v81 offset:2048
	ds_read_b128 v[164:167], v145 offset:32768
	ds_read_b128 v[168:171], v145 offset:34816
	ds_read_b128 v[174:177], v145 offset:36864
	ds_read_b128 v[182:185], v145 offset:38912
	ds_read_b128 v[188:191], v145 offset:40960
	ds_read_b128 v[192:195], v145 offset:43008
	ds_read_b128 v[208:211], v145 offset:45056
	ds_read_b128 v[212:215], v145 offset:47104
	ds_read_b128 v[156:159], v81 offset:16384
	ds_read_b128 v[160:163], v81 offset:18432
	s_waitcnt lgkmcnt(0)
	s_lshl_b32 m0, s64, 2
	s_add_i32 m0, m0, 0x0
	s_nop 0
	global_load_lds_dwordx4 v77, s[50:51]
	s_add_u32 s50, s50, 0x4000
	s_addc_u32 s51, s51, 0
	s_lshl_b32 m0, s64, 2
	s_add_i32 m0, m0, 0x400
	s_nop 0
	global_load_lds_dwordx4 v78, s[50:51]
	s_add_u32 s50, s50, 0x4000
	s_addc_u32 s51, s51, 0
	s_lshl_b32 m0, s64, 2
	s_add_i32 m0, m0, 0x800
	s_nop 0
	global_load_lds_dwordx4 v77, s[50:51]
	s_add_u32 s50, s50, 0x4000
	s_addc_u32 s51, s51, 0
	s_lshl_b32 m0, s64, 2
	s_add_i32 m0, m0, 0xc00
	s_nop 0
	global_load_lds_dwordx4 v78, s[50:51]
	s_sub_u32 s50, s50, 0xbf80
	s_subb_u32 s51, s51, 0
	s_lshl_b32 m0, s64, 2
	s_add_i32 m0, m0, 0x4000
	s_nop 0
	global_load_lds_dwordx4 v77, s[52:53]
	s_add_u32 s52, s52, 0x4000
	s_addc_u32 s53, s53, 0
	s_lshl_b32 m0, s64, 2
	s_add_i32 m0, m0, 0x4400
	s_nop 0
	global_load_lds_dwordx4 v78, s[52:53]
	s_add_u32 s52, s52, 0x4000
	s_addc_u32 s53, s53, 0
	s_lshl_b32 m0, s64, 2
	s_add_i32 m0, m0, 0x4800
	s_nop 0
	global_load_lds_dwordx4 v77, s[52:53]
	s_add_u32 s52, s52, 0x4000
	s_addc_u32 s53, s53, 0
	s_lshl_b32 m0, s64, 2
	s_add_i32 m0, m0, 0x4c00
	s_nop 0
	global_load_lds_dwordx4 v78, s[52:53]
	s_sub_u32 s52, s52, 0xbf80
	s_subb_u32 s53, s53, 0
	s_setprio 1
	v_mfma_f32_16x16x32_bf16 v[62:65], v[164:167], v[148:151], v[62:65]
	v_mfma_f32_16x16x32_bf16 v[54:57], v[168:171], v[148:151], v[54:57]
	v_mfma_f32_16x16x32_bf16 v[58:61], v[174:177], v[148:151], v[58:61]
	v_mfma_f32_16x16x32_bf16 v[50:53], v[182:185], v[148:151], v[50:53]
	v_mfma_f32_16x16x32_bf16 v[46:49], v[188:191], v[148:151], v[46:49]
	v_mfma_f32_16x16x32_bf16 v[38:41], v[192:195], v[148:151], v[38:41]
	v_mfma_f32_16x16x32_bf16 v[42:45], v[208:211], v[148:151], v[42:45]
	v_mfma_f32_16x16x32_bf16 v[34:37], v[212:215], v[148:151], v[34:37]
	v_mfma_f32_16x16x32_bf16 v[30:33], v[164:167], v[152:155], v[30:33]
	v_mfma_f32_16x16x32_bf16 v[22:25], v[168:171], v[152:155], v[22:25]
	v_mfma_f32_16x16x32_bf16 v[26:29], v[174:177], v[152:155], v[26:29]
	v_mfma_f32_16x16x32_bf16 v[18:21], v[182:185], v[152:155], v[18:21]
	v_mfma_f32_16x16x32_bf16 v[14:17], v[188:191], v[152:155], v[14:17]
	v_mfma_f32_16x16x32_bf16 v[6:9], v[192:195], v[152:155], v[6:9]
	v_mfma_f32_16x16x32_bf16 v[10:13], v[208:211], v[152:155], v[10:13]
	v_mfma_f32_16x16x32_bf16 v[2:5], v[212:215], v[152:155], v[2:5]
	s_waitcnt lgkmcnt(0)
	v_mfma_f32_16x16x32_bf16 v[66:69], v[164:167], v[156:159], v[66:69]
	v_mfma_f32_16x16x32_bf16 v[70:73], v[168:171], v[156:159], v[70:73]
	v_mfma_f32_16x16x32_bf16 v[82:85], v[174:177], v[156:159], v[82:85]
	v_mfma_f32_16x16x32_bf16 v[86:89], v[182:185], v[156:159], v[86:89]
	v_mfma_f32_16x16x32_bf16 v[90:93], v[188:191], v[156:159], v[90:93]
	v_mfma_f32_16x16x32_bf16 v[94:97], v[192:195], v[156:159], v[94:97]
	v_mfma_f32_16x16x32_bf16 v[98:101], v[208:211], v[156:159], v[98:101]
	v_mfma_f32_16x16x32_bf16 v[102:105], v[212:215], v[156:159], v[102:105]
	v_mfma_f32_16x16x32_bf16 v[106:109], v[164:167], v[160:163], v[106:109]
	v_mfma_f32_16x16x32_bf16 v[110:113], v[168:171], v[160:163], v[110:113]
	v_mfma_f32_16x16x32_bf16 v[114:117], v[174:177], v[160:163], v[114:117]
	v_mfma_f32_16x16x32_bf16 v[118:121], v[182:185], v[160:163], v[118:121]
	v_mfma_f32_16x16x32_bf16 v[122:125], v[188:191], v[160:163], v[122:125]
	v_mfma_f32_16x16x32_bf16 v[126:129], v[192:195], v[160:163], v[126:129]
	v_mfma_f32_16x16x32_bf16 v[136:139], v[208:211], v[160:163], v[136:139]
	v_mfma_f32_16x16x32_bf16 v[140:143], v[212:215], v[160:163], v[140:143]
	s_setprio 0
	s_waitcnt vmcnt(0)
	s_barrier
	ds_read_b128 v[148:151], v80 offset:0
	ds_read_b128 v[152:155], v80 offset:2048
	ds_read_b128 v[164:167], v144 offset:49152
	ds_read_b128 v[168:171], v144 offset:51200
	ds_read_b128 v[174:177], v144 offset:53248
	ds_read_b128 v[182:185], v144 offset:55296
	ds_read_b128 v[188:191], v144 offset:57344
	ds_read_b128 v[192:195], v144 offset:59392
	ds_read_b128 v[208:211], v144 offset:61440
	ds_read_b128 v[212:215], v144 offset:63488
	ds_read_b128 v[156:159], v80 offset:16384
	ds_read_b128 v[160:163], v80 offset:18432
	s_setprio 1
	s_waitcnt lgkmcnt(2)
	v_mfma_f32_16x16x32_bf16 v[62:65], v[164:167], v[148:151], v[62:65]
	v_mfma_f32_16x16x32_bf16 v[54:57], v[168:171], v[148:151], v[54:57]
	v_mfma_f32_16x16x32_bf16 v[58:61], v[174:177], v[148:151], v[58:61]
	v_mfma_f32_16x16x32_bf16 v[50:53], v[182:185], v[148:151], v[50:53]
	v_mfma_f32_16x16x32_bf16 v[46:49], v[188:191], v[148:151], v[46:49]
	v_mfma_f32_16x16x32_bf16 v[38:41], v[192:195], v[148:151], v[38:41]
	v_mfma_f32_16x16x32_bf16 v[42:45], v[208:211], v[148:151], v[42:45]
	v_mfma_f32_16x16x32_bf16 v[34:37], v[212:215], v[148:151], v[34:37]
	v_mfma_f32_16x16x32_bf16 v[30:33], v[164:167], v[152:155], v[30:33]
	v_mfma_f32_16x16x32_bf16 v[22:25], v[168:171], v[152:155], v[22:25]
	v_mfma_f32_16x16x32_bf16 v[26:29], v[174:177], v[152:155], v[26:29]
	v_mfma_f32_16x16x32_bf16 v[18:21], v[182:185], v[152:155], v[18:21]
	v_mfma_f32_16x16x32_bf16 v[14:17], v[188:191], v[152:155], v[14:17]
	v_mfma_f32_16x16x32_bf16 v[6:9], v[192:195], v[152:155], v[6:9]
	v_mfma_f32_16x16x32_bf16 v[10:13], v[208:211], v[152:155], v[10:13]
	v_mfma_f32_16x16x32_bf16 v[2:5], v[212:215], v[152:155], v[2:5]
	s_waitcnt lgkmcnt(0)
	v_mfma_f32_16x16x32_bf16 v[66:69], v[164:167], v[156:159], v[66:69]
	v_mfma_f32_16x16x32_bf16 v[70:73], v[168:171], v[156:159], v[70:73]
	v_mfma_f32_16x16x32_bf16 v[82:85], v[174:177], v[156:159], v[82:85]
	v_mfma_f32_16x16x32_bf16 v[86:89], v[182:185], v[156:159], v[86:89]
	v_mfma_f32_16x16x32_bf16 v[90:93], v[188:191], v[156:159], v[90:93]
	v_mfma_f32_16x16x32_bf16 v[94:97], v[192:195], v[156:159], v[94:97]
	v_mfma_f32_16x16x32_bf16 v[98:101], v[208:211], v[156:159], v[98:101]
	v_mfma_f32_16x16x32_bf16 v[102:105], v[212:215], v[156:159], v[102:105]
	v_mfma_f32_16x16x32_bf16 v[106:109], v[164:167], v[160:163], v[106:109]
	v_mfma_f32_16x16x32_bf16 v[110:113], v[168:171], v[160:163], v[110:113]
	v_mfma_f32_16x16x32_bf16 v[114:117], v[174:177], v[160:163], v[114:117]
	v_mfma_f32_16x16x32_bf16 v[118:121], v[182:185], v[160:163], v[118:121]
	v_mfma_f32_16x16x32_bf16 v[122:125], v[188:191], v[160:163], v[122:125]
	v_mfma_f32_16x16x32_bf16 v[126:129], v[192:195], v[160:163], v[126:129]
	v_mfma_f32_16x16x32_bf16 v[136:139], v[208:211], v[160:163], v[136:139]
	v_mfma_f32_16x16x32_bf16 v[140:143], v[212:215], v[160:163], v[140:143]
	s_setprio 0
	ds_read_b128 v[148:151], v81 offset:0
	ds_read_b128 v[152:155], v81 offset:2048
	ds_read_b128 v[164:167], v145 offset:49152
	ds_read_b128 v[168:171], v145 offset:51200
	ds_read_b128 v[174:177], v145 offset:53248
	ds_read_b128 v[182:185], v145 offset:55296
	ds_read_b128 v[188:191], v145 offset:57344
	ds_read_b128 v[192:195], v145 offset:59392
	ds_read_b128 v[208:211], v145 offset:61440
	ds_read_b128 v[212:215], v145 offset:63488
	ds_read_b128 v[156:159], v81 offset:16384
	ds_read_b128 v[160:163], v81 offset:18432
	s_setprio 1
	s_waitcnt lgkmcnt(2)
	v_mfma_f32_16x16x32_bf16 v[62:65], v[164:167], v[148:151], v[62:65]
	v_mfma_f32_16x16x32_bf16 v[54:57], v[168:171], v[148:151], v[54:57]
	v_mfma_f32_16x16x32_bf16 v[58:61], v[174:177], v[148:151], v[58:61]
	v_mfma_f32_16x16x32_bf16 v[50:53], v[182:185], v[148:151], v[50:53]
	v_mfma_f32_16x16x32_bf16 v[46:49], v[188:191], v[148:151], v[46:49]
	v_mfma_f32_16x16x32_bf16 v[38:41], v[192:195], v[148:151], v[38:41]
	v_mfma_f32_16x16x32_bf16 v[42:45], v[208:211], v[148:151], v[42:45]
	v_mfma_f32_16x16x32_bf16 v[34:37], v[212:215], v[148:151], v[34:37]
	v_mfma_f32_16x16x32_bf16 v[30:33], v[164:167], v[152:155], v[30:33]
	v_mfma_f32_16x16x32_bf16 v[22:25], v[168:171], v[152:155], v[22:25]
	v_mfma_f32_16x16x32_bf16 v[26:29], v[174:177], v[152:155], v[26:29]
	v_mfma_f32_16x16x32_bf16 v[18:21], v[182:185], v[152:155], v[18:21]
	v_mfma_f32_16x16x32_bf16 v[14:17], v[188:191], v[152:155], v[14:17]
	v_mfma_f32_16x16x32_bf16 v[6:9], v[192:195], v[152:155], v[6:9]
	v_mfma_f32_16x16x32_bf16 v[10:13], v[208:211], v[152:155], v[10:13]
	v_mfma_f32_16x16x32_bf16 v[2:5], v[212:215], v[152:155], v[2:5]
	s_waitcnt lgkmcnt(0)
	v_mfma_f32_16x16x32_bf16 v[66:69], v[164:167], v[156:159], v[66:69]
	v_mfma_f32_16x16x32_bf16 v[70:73], v[168:171], v[156:159], v[70:73]
	v_mfma_f32_16x16x32_bf16 v[82:85], v[174:177], v[156:159], v[82:85]
	v_mfma_f32_16x16x32_bf16 v[86:89], v[182:185], v[156:159], v[86:89]
	v_mfma_f32_16x16x32_bf16 v[90:93], v[188:191], v[156:159], v[90:93]
	v_mfma_f32_16x16x32_bf16 v[94:97], v[192:195], v[156:159], v[94:97]
	v_mfma_f32_16x16x32_bf16 v[98:101], v[208:211], v[156:159], v[98:101]
	v_mfma_f32_16x16x32_bf16 v[102:105], v[212:215], v[156:159], v[102:105]
	v_mfma_f32_16x16x32_bf16 v[106:109], v[164:167], v[160:163], v[106:109]
	v_mfma_f32_16x16x32_bf16 v[110:113], v[168:171], v[160:163], v[110:113]
	v_mfma_f32_16x16x32_bf16 v[114:117], v[174:177], v[160:163], v[114:117]
	v_mfma_f32_16x16x32_bf16 v[118:121], v[182:185], v[160:163], v[118:121]
	v_mfma_f32_16x16x32_bf16 v[122:125], v[188:191], v[160:163], v[122:125]
	v_mfma_f32_16x16x32_bf16 v[126:129], v[192:195], v[160:163], v[126:129]
	v_mfma_f32_16x16x32_bf16 v[136:139], v[208:211], v[160:163], v[136:139]
	v_mfma_f32_16x16x32_bf16 v[140:143], v[212:215], v[160:163], v[140:143]
	s_setprio 0
	s_nop 7
	s_nop 7
	s_nop 7
	s_add_i32 s48, s48, 1
	s_mov_b32 s39, 0
	v_readlane_b32 s30, v249, 0
	s_nop 0
	s_and_b32 s31, s30, 7
	s_lshr_b32 s30, s30, 3
	s_cmp_lt_u32 s30, 32
	s_cselect_b32 s35, 6, 5
	s_cmp_lt_u32 s48, s35
	s_cbranch_scc0 .Lf2_c1_extra
	s_lshl_b32 s33, s48, 6
	s_add_i32 s33, s33, s30
	s_cmp_ge_u32 s33, 0xb0
	s_cselect_b32 s34, 1, 0
	s_mul_i32 s36, s34, 0xb0
	s_sub_i32 s33, s33, s36
	s_lshr_b32 s37, s33, 2
	s_and_b32 s33, s33, 3
	s_lshl_b32 s34, s34, 3
	s_add_i32 s33, s33, s34
	s_lshl_b32 s33, s33, 3
	s_add_i32 s36, s33, s31
	s_add_i32 s38, s36, 32
	s_branch .Lf2_c1_have

.Lf2_c1_have:
	s_mov_b32 s39, 2
	s_lshl_b32 s30, s36, 18
	s_add_u32 s50, s6, s30
	s_addc_u32 s51, s7, 0
	s_lshl_b32 s30, s38, 18
	s_add_u32 s52, s6, s30
	s_addc_u32 s53, s7, 0
	s_lshl_b32 s30, s37, 18
	s_add_u32 s58, s19, s30
	s_addc_u32 s59, s20, 0
	s_barrier
	s_lshl_b32 m0, s64, 2
	s_add_i32 m0, m0, 0x0
	s_nop 0
	global_load_lds_dwordx4 v77, s[50:51]
	s_add_u32 s50, s50, 0x4000
	s_addc_u32 s51, s51, 0
	s_lshl_b32 m0, s64, 2
	s_add_i32 m0, m0, 0x400
	s_nop 0
	global_load_lds_dwordx4 v78, s[50:51]
	s_add_u32 s50, s50, 0x4000
	s_addc_u32 s51, s51, 0
	s_lshl_b32 m0, s64, 2
	s_add_i32 m0, m0, 0x800
	s_nop 0
	global_load_lds_dwordx4 v77, s[50:51]
	s_add_u32 s50, s50, 0x4000
	s_addc_u32 s51, s51, 0
	s_lshl_b32 m0, s64, 2
	s_add_i32 m0, m0, 0xc00
	s_nop 0
	global_load_lds_dwordx4 v78, s[50:51]
	s_sub_u32 s50, s50, 0xbf80
	s_subb_u32 s51, s51, 0
	s_lshl_b32 m0, s64, 2
	s_add_i32 m0, m0, 0x4000
	s_nop 0
	global_load_lds_dwordx4 v77, s[52:53]
	s_add_u32 s52, s52, 0x4000
	s_addc_u32 s53, s53, 0
	s_lshl_b32 m0, s64, 2
	s_add_i32 m0, m0, 0x4400
	s_nop 0
	global_load_lds_dwordx4 v78, s[52:53]
	s_add_u32 s52, s52, 0x4000
	s_addc_u32 s53, s53, 0
	s_lshl_b32 m0, s64, 2
	s_add_i32 m0, m0, 0x4800
	s_nop 0
	global_load_lds_dwordx4 v77, s[52:53]
	s_add_u32 s52, s52, 0x4000
	s_addc_u32 s53, s53, 0
	s_lshl_b32 m0, s64, 2
	s_add_i32 m0, m0, 0x4c00
	s_nop 0
	global_load_lds_dwordx4 v78, s[52:53]
	s_sub_u32 s52, s52, 0xbf80
	s_subb_u32 s53, s53, 0
	s_add_i32 m0, s64, 0x8000
	s_nop 0
	global_load_lds_dwordx4 v76, s[58:59]
	s_add_u32 s58, s58, 0x10000
	s_addc_u32 s59, s59, 0
	s_add_i32 m0, s64, 0x9000
	s_nop 0
	global_load_lds_dwordx4 v76, s[58:59]
	s_add_u32 s58, s58, 0x10000
	s_addc_u32 s59, s59, 0
	s_add_i32 m0, s64, 0xa000
	s_nop 0
	global_load_lds_dwordx4 v76, s[58:59]
	s_add_u32 s58, s58, 0x10000
	s_addc_u32 s59, s59, 0
	s_add_i32 m0, s64, 0xb000
	s_nop 0
	global_load_lds_dwordx4 v76, s[58:59]
	s_sub_u32 s58, s58, 0x2ff80
	s_subb_u32 s59, s59, 0
.Lf2_nopf:
	s_load_dwordx2 s[40:41], s[84:85], 0x1c0
	v_lshrrev_b32_e32 v148, 6, v196
	v_and_b32_e32 v149, 15, v196
	v_lshl_or_b32 v148, v148, 5, v149
	v_mul_u32_u24_e32 v148, 0x1600, v148
	v_mov_b32_e32 v149, 0
	v_bfe_u32 v150, v196, 4, 2
	v_lshlrev_b32_e32 v149, 6, v149
	v_lshl_or_b32 v149, v150, 3, v149
	v_and_b32_e32 v150, 1, v150
	v_mul_u32_u24_e32 v150, 24, v150
	v_add3_u32 v156, v148, v149, v150
	v_add_u32_e32 v157, 0x16000, v156
	v_add_u32_e32 v158, 0x2c000, v156
	v_add_u32_e32 v159, 0x42000, v156
	s_waitcnt lgkmcnt(0)
	s_mul_i32 s30, s8, 0xb0000
	s_lshl_b32 s31, s21, 7
	s_add_i32 s30, s30, s31
	s_add_u32 s42, s40, s30
	s_addc_u32 s43, s41, 0
	v_mul_f32_e32 v148, 0xbfb8aa3b, v62
	v_mul_f32_e32 v149, 0xbfb8aa3b, v63
	v_mul_f32_e32 v150, 0xbfb8aa3b, v64
	v_mul_f32_e32 v151, 0xbfb8aa3b, v65
	v_exp_f32_e32 v148, v148
	v_exp_f32_e32 v149, v149
	v_exp_f32_e32 v150, v150
	v_exp_f32_e32 v151, v151
	v_add_f32_e32 v148, 1.0, v148
	v_add_f32_e32 v149, 1.0, v149
	v_add_f32_e32 v150, 1.0, v150
	v_add_f32_e32 v151, 1.0, v151
	v_rcp_f32_e32 v148, v148
	v_rcp_f32_e32 v149, v149
	v_rcp_f32_e32 v150, v150
	v_rcp_f32_e32 v151, v151
	s_nop 0
	v_pk_mul_f32 v[62:63], v[62:63], v[148:149]
	v_pk_mul_f32 v[64:65], v[64:65], v[150:151]
	v_pk_mul_f32 v[58:59], v[58:59], v[62:63]
	v_pk_mul_f32 v[60:61], v[60:61], v[64:65]
	v_mul_f32_e32 v148, 0xbfb8aa3b, v54
	v_mul_f32_e32 v149, 0xbfb8aa3b, v55
	v_mul_f32_e32 v150, 0xbfb8aa3b, v56
	v_mul_f32_e32 v151, 0xbfb8aa3b, v57
	v_exp_f32_e32 v148, v148
	v_exp_f32_e32 v149, v149
	v_exp_f32_e32 v150, v150
	v_exp_f32_e32 v151, v151
	v_add_f32_e32 v148, 1.0, v148
	v_add_f32_e32 v149, 1.0, v149
	v_add_f32_e32 v150, 1.0, v150
	v_add_f32_e32 v151, 1.0, v151
	v_rcp_f32_e32 v148, v148
	v_rcp_f32_e32 v149, v149
	v_rcp_f32_e32 v150, v150
	v_rcp_f32_e32 v151, v151
	s_nop 0
	v_pk_mul_f32 v[54:55], v[54:55], v[148:149]
	v_pk_mul_f32 v[56:57], v[56:57], v[150:151]
	v_pk_mul_f32 v[50:51], v[50:51], v[54:55]
	v_pk_mul_f32 v[52:53], v[52:53], v[56:57]
	v_cvt_pk_bf16_f32 v164, v58, v59
	v_cvt_pk_bf16_f32 v165, v60, v61
	v_cvt_pk_bf16_f32 v166, v50, v51
	v_cvt_pk_bf16_f32 v167, v52, v53
	s_nop 1
	v_permlane16_swap_b32 v164, v166
	v_permlane16_swap_b32 v165, v167
	s_nop 1
	global_store_dwordx4 v156, v[164:167], s[42:43]
	v_mul_f32_e32 v148, 0xbfb8aa3b, v46
	v_mul_f32_e32 v149, 0xbfb8aa3b, v47
	v_mul_f32_e32 v150, 0xbfb8aa3b, v48
	v_mul_f32_e32 v151, 0xbfb8aa3b, v49
	v_exp_f32_e32 v148, v148
	v_exp_f32_e32 v149, v149
	v_exp_f32_e32 v150, v150
	v_exp_f32_e32 v151, v151
	v_add_f32_e32 v148, 1.0, v148
	v_add_f32_e32 v149, 1.0, v149
	v_add_f32_e32 v150, 1.0, v150
	v_add_f32_e32 v151, 1.0, v151
	v_rcp_f32_e32 v148, v148
	v_rcp_f32_e32 v149, v149
	v_rcp_f32_e32 v150, v150
	v_rcp_f32_e32 v151, v151
	s_nop 0
	v_pk_mul_f32 v[46:47], v[46:47], v[148:149]
	v_pk_mul_f32 v[48:49], v[48:49], v[150:151]
	v_pk_mul_f32 v[42:43], v[42:43], v[46:47]
	v_pk_mul_f32 v[44:45], v[44:45], v[48:49]
	v_mul_f32_e32 v148, 0xbfb8aa3b, v38
	v_mul_f32_e32 v149, 0xbfb8aa3b, v39
	v_mul_f32_e32 v150, 0xbfb8aa3b, v40
	v_mul_f32_e32 v151, 0xbfb8aa3b, v41
	v_exp_f32_e32 v148, v148
	v_exp_f32_e32 v149, v149
	v_exp_f32_e32 v150, v150
	v_exp_f32_e32 v151, v151
	v_add_f32_e32 v148, 1.0, v148
	v_add_f32_e32 v149, 1.0, v149
	v_add_f32_e32 v150, 1.0, v150
	v_add_f32_e32 v151, 1.0, v151
	v_rcp_f32_e32 v148, v148
	v_rcp_f32_e32 v149, v149
	v_rcp_f32_e32 v150, v150
	v_rcp_f32_e32 v151, v151
	s_nop 0
	v_pk_mul_f32 v[38:39], v[38:39], v[148:149]
	v_pk_mul_f32 v[40:41], v[40:41], v[150:151]
	v_pk_mul_f32 v[34:35], v[34:35], v[38:39]
	v_pk_mul_f32 v[36:37], v[36:37], v[40:41]
	v_cvt_pk_bf16_f32 v168, v42, v43
	v_cvt_pk_bf16_f32 v169, v44, v45
	v_cvt_pk_bf16_f32 v170, v34, v35
	v_cvt_pk_bf16_f32 v171, v36, v37
	s_nop 1
	v_permlane16_swap_b32 v168, v170
	v_permlane16_swap_b32 v169, v171
	s_nop 1
	global_store_dwordx4 v156, v[168:171], s[42:43] offset:64
	v_mul_f32_e32 v148, 0xbfb8aa3b, v30
	v_mul_f32_e32 v149, 0xbfb8aa3b, v31
	v_mul_f32_e32 v150, 0xbfb8aa3b, v32
	v_mul_f32_e32 v151, 0xbfb8aa3b, v33
	v_exp_f32_e32 v148, v148
	v_exp_f32_e32 v149, v149
	v_exp_f32_e32 v150, v150
	v_exp_f32_e32 v151, v151
	v_add_f32_e32 v148, 1.0, v148
	v_add_f32_e32 v149, 1.0, v149
	v_add_f32_e32 v150, 1.0, v150
	v_add_f32_e32 v151, 1.0, v151
	v_rcp_f32_e32 v148, v148
	v_rcp_f32_e32 v149, v149
	v_rcp_f32_e32 v150, v150
	v_rcp_f32_e32 v151, v151
	s_nop 0
	v_pk_mul_f32 v[30:31], v[30:31], v[148:149]
	v_pk_mul_f32 v[32:33], v[32:33], v[150:151]
	v_pk_mul_f32 v[26:27], v[26:27], v[30:31]
	v_pk_mul_f32 v[28:29], v[28:29], v[32:33]
	v_mul_f32_e32 v148, 0xbfb8aa3b, v22
	v_mul_f32_e32 v149, 0xbfb8aa3b, v23
	v_mul_f32_e32 v150, 0xbfb8aa3b, v24
	v_mul_f32_e32 v151, 0xbfb8aa3b, v25
	v_exp_f32_e32 v148, v148
	v_exp_f32_e32 v149, v149
	v_exp_f32_e32 v150, v150
	v_exp_f32_e32 v151, v151
	v_add_f32_e32 v148, 1.0, v148
	v_add_f32_e32 v149, 1.0, v149
	v_add_f32_e32 v150, 1.0, v150
	v_add_f32_e32 v151, 1.0, v151
	v_rcp_f32_e32 v148, v148
	v_rcp_f32_e32 v149, v149
	v_rcp_f32_e32 v150, v150
	v_rcp_f32_e32 v151, v151
	s_nop 0
	v_pk_mul_f32 v[22:23], v[22:23], v[148:149]
	v_pk_mul_f32 v[24:25], v[24:25], v[150:151]
	v_pk_mul_f32 v[18:19], v[18:19], v[22:23]
	v_pk_mul_f32 v[20:21], v[20:21], v[24:25]
	v_cvt_pk_bf16_f32 v164, v26, v27
	v_cvt_pk_bf16_f32 v165, v28, v29
	v_cvt_pk_bf16_f32 v166, v18, v19
	v_cvt_pk_bf16_f32 v167, v20, v21
	s_nop 1
	v_permlane16_swap_b32 v164, v166
	v_permlane16_swap_b32 v165, v167
	s_nop 1
	global_store_dwordx4 v157, v[164:167], s[42:43]
	v_mul_f32_e32 v148, 0xbfb8aa3b, v14
	v_mul_f32_e32 v149, 0xbfb8aa3b, v15
	v_mul_f32_e32 v150, 0xbfb8aa3b, v16
	v_mul_f32_e32 v151, 0xbfb8aa3b, v17
	v_exp_f32_e32 v148, v148
	v_exp_f32_e32 v149, v149
	v_exp_f32_e32 v150, v150
	v_exp_f32_e32 v151, v151
	v_add_f32_e32 v148, 1.0, v148
	v_add_f32_e32 v149, 1.0, v149
	v_add_f32_e32 v150, 1.0, v150
	v_add_f32_e32 v151, 1.0, v151
	v_rcp_f32_e32 v148, v148
	v_rcp_f32_e32 v149, v149
	v_rcp_f32_e32 v150, v150
	v_rcp_f32_e32 v151, v151
	s_nop 0
	v_pk_mul_f32 v[14:15], v[14:15], v[148:149]
	v_pk_mul_f32 v[16:17], v[16:17], v[150:151]
	v_pk_mul_f32 v[10:11], v[10:11], v[14:15]
	v_pk_mul_f32 v[12:13], v[12:13], v[16:17]
	v_mul_f32_e32 v148, 0xbfb8aa3b, v6
	v_mul_f32_e32 v149, 0xbfb8aa3b, v7
	v_mul_f32_e32 v150, 0xbfb8aa3b, v8
	v_mul_f32_e32 v151, 0xbfb8aa3b, v9
	v_exp_f32_e32 v148, v148
	v_exp_f32_e32 v149, v149
	v_exp_f32_e32 v150, v150
	v_exp_f32_e32 v151, v151
	v_add_f32_e32 v148, 1.0, v148
	v_add_f32_e32 v149, 1.0, v149
	v_add_f32_e32 v150, 1.0, v150
	v_add_f32_e32 v151, 1.0, v151
	v_rcp_f32_e32 v148, v148
	v_rcp_f32_e32 v149, v149
	v_rcp_f32_e32 v150, v150
	v_rcp_f32_e32 v151, v151
	s_nop 0
	v_pk_mul_f32 v[6:7], v[6:7], v[148:149]
	v_pk_mul_f32 v[8:9], v[8:9], v[150:151]
	v_pk_mul_f32 v[2:3], v[2:3], v[6:7]
	v_pk_mul_f32 v[4:5], v[4:5], v[8:9]
	v_cvt_pk_bf16_f32 v168, v10, v11
	v_cvt_pk_bf16_f32 v169, v12, v13
	v_cvt_pk_bf16_f32 v170, v2, v3
	v_cvt_pk_bf16_f32 v171, v4, v5
	s_nop 1
	v_permlane16_swap_b32 v168, v170
	v_permlane16_swap_b32 v169, v171
	s_nop 1
	global_store_dwordx4 v157, v[168:171], s[42:43] offset:64
	s_mul_i32 s30, s49, 0xb0000
	s_lshl_b32 s31, s21, 7
	s_add_i32 s30, s30, s31
	s_add_u32 s42, s40, s30
	s_addc_u32 s43, s41, 0
	v_mul_f32_e32 v148, 0xbfb8aa3b, v66
	v_mul_f32_e32 v149, 0xbfb8aa3b, v67
	v_mul_f32_e32 v150, 0xbfb8aa3b, v68
	v_mul_f32_e32 v151, 0xbfb8aa3b, v69
	v_exp_f32_e32 v148, v148
	v_exp_f32_e32 v149, v149
	v_exp_f32_e32 v150, v150
	v_exp_f32_e32 v151, v151
	v_add_f32_e32 v148, 1.0, v148
	v_add_f32_e32 v149, 1.0, v149
	v_add_f32_e32 v150, 1.0, v150
	v_add_f32_e32 v151, 1.0, v151
	v_rcp_f32_e32 v148, v148
	v_rcp_f32_e32 v149, v149
	v_rcp_f32_e32 v150, v150
	v_rcp_f32_e32 v151, v151
	s_nop 0
	v_pk_mul_f32 v[66:67], v[66:67], v[148:149]
	v_pk_mul_f32 v[68:69], v[68:69], v[150:151]
	v_pk_mul_f32 v[82:83], v[82:83], v[66:67]
	v_pk_mul_f32 v[84:85], v[84:85], v[68:69]
	v_mul_f32_e32 v148, 0xbfb8aa3b, v70
	v_mul_f32_e32 v149, 0xbfb8aa3b, v71
	v_mul_f32_e32 v150, 0xbfb8aa3b, v72
	v_mul_f32_e32 v151, 0xbfb8aa3b, v73
	v_exp_f32_e32 v148, v148
	v_exp_f32_e32 v149, v149
	v_exp_f32_e32 v150, v150
	v_exp_f32_e32 v151, v151
	v_add_f32_e32 v148, 1.0, v148
	v_add_f32_e32 v149, 1.0, v149
	v_add_f32_e32 v150, 1.0, v150
	v_add_f32_e32 v151, 1.0, v151
	v_rcp_f32_e32 v148, v148
	v_rcp_f32_e32 v149, v149
	v_rcp_f32_e32 v150, v150
	v_rcp_f32_e32 v151, v151
	s_nop 0
	v_pk_mul_f32 v[70:71], v[70:71], v[148:149]
	v_pk_mul_f32 v[72:73], v[72:73], v[150:151]
	v_pk_mul_f32 v[86:87], v[86:87], v[70:71]
	v_pk_mul_f32 v[88:89], v[88:89], v[72:73]
	v_cvt_pk_bf16_f32 v164, v82, v83
	v_cvt_pk_bf16_f32 v165, v84, v85
	v_cvt_pk_bf16_f32 v166, v86, v87
	v_cvt_pk_bf16_f32 v167, v88, v89
	s_nop 1
	v_permlane16_swap_b32 v164, v166
	v_permlane16_swap_b32 v165, v167
	s_nop 1
	global_store_dwordx4 v156, v[164:167], s[42:43]
	v_mul_f32_e32 v148, 0xbfb8aa3b, v90
	v_mul_f32_e32 v149, 0xbfb8aa3b, v91
	v_mul_f32_e32 v150, 0xbfb8aa3b, v92
	v_mul_f32_e32 v151, 0xbfb8aa3b, v93
	v_exp_f32_e32 v148, v148
	v_exp_f32_e32 v149, v149
	v_exp_f32_e32 v150, v150
	v_exp_f32_e32 v151, v151
	v_add_f32_e32 v148, 1.0, v148
	v_add_f32_e32 v149, 1.0, v149
	v_add_f32_e32 v150, 1.0, v150
	v_add_f32_e32 v151, 1.0, v151
	v_rcp_f32_e32 v148, v148
	v_rcp_f32_e32 v149, v149
	v_rcp_f32_e32 v150, v150
	v_rcp_f32_e32 v151, v151
	s_nop 0
	v_pk_mul_f32 v[90:91], v[90:91], v[148:149]
	v_pk_mul_f32 v[92:93], v[92:93], v[150:151]
	v_pk_mul_f32 v[98:99], v[98:99], v[90:91]
	v_pk_mul_f32 v[100:101], v[100:101], v[92:93]
	v_mul_f32_e32 v148, 0xbfb8aa3b, v94
	v_mul_f32_e32 v149, 0xbfb8aa3b, v95
	v_mul_f32_e32 v150, 0xbfb8aa3b, v96
	v_mul_f32_e32 v151, 0xbfb8aa3b, v97
	v_exp_f32_e32 v148, v148
	v_exp_f32_e32 v149, v149
	v_exp_f32_e32 v150, v150
	v_exp_f32_e32 v151, v151
	v_add_f32_e32 v148, 1.0, v148
	v_add_f32_e32 v149, 1.0, v149
	v_add_f32_e32 v150, 1.0, v150
	v_add_f32_e32 v151, 1.0, v151
	v_rcp_f32_e32 v148, v148
	v_rcp_f32_e32 v149, v149
	v_rcp_f32_e32 v150, v150
	v_rcp_f32_e32 v151, v151
	s_nop 0
	v_pk_mul_f32 v[94:95], v[94:95], v[148:149]
	v_pk_mul_f32 v[96:97], v[96:97], v[150:151]
	v_pk_mul_f32 v[102:103], v[102:103], v[94:95]
	v_pk_mul_f32 v[104:105], v[104:105], v[96:97]
	v_cvt_pk_bf16_f32 v168, v98, v99
	v_cvt_pk_bf16_f32 v169, v100, v101
	v_cvt_pk_bf16_f32 v170, v102, v103
	v_cvt_pk_bf16_f32 v171, v104, v105
	s_nop 1
	v_permlane16_swap_b32 v168, v170
	v_permlane16_swap_b32 v169, v171
	s_nop 1
	global_store_dwordx4 v156, v[168:171], s[42:43] offset:64
	v_mul_f32_e32 v148, 0xbfb8aa3b, v106
	v_mul_f32_e32 v149, 0xbfb8aa3b, v107
	v_mul_f32_e32 v150, 0xbfb8aa3b, v108
	v_mul_f32_e32 v151, 0xbfb8aa3b, v109
	v_exp_f32_e32 v148, v148
	v_exp_f32_e32 v149, v149
	v_exp_f32_e32 v150, v150
	v_exp_f32_e32 v151, v151
	v_add_f32_e32 v148, 1.0, v148
	v_add_f32_e32 v149, 1.0, v149
	v_add_f32_e32 v150, 1.0, v150
	v_add_f32_e32 v151, 1.0, v151
	v_rcp_f32_e32 v148, v148
	v_rcp_f32_e32 v149, v149
	v_rcp_f32_e32 v150, v150
	v_rcp_f32_e32 v151, v151
	s_nop 0
	v_pk_mul_f32 v[106:107], v[106:107], v[148:149]
	v_pk_mul_f32 v[108:109], v[108:109], v[150:151]
	v_pk_mul_f32 v[114:115], v[114:115], v[106:107]
	v_pk_mul_f32 v[116:117], v[116:117], v[108:109]
	v_mul_f32_e32 v148, 0xbfb8aa3b, v110
	v_mul_f32_e32 v149, 0xbfb8aa3b, v111
	v_mul_f32_e32 v150, 0xbfb8aa3b, v112
	v_mul_f32_e32 v151, 0xbfb8aa3b, v113
	v_exp_f32_e32 v148, v148
	v_exp_f32_e32 v149, v149
	v_exp_f32_e32 v150, v150
	v_exp_f32_e32 v151, v151
	v_add_f32_e32 v148, 1.0, v148
	v_add_f32_e32 v149, 1.0, v149
	v_add_f32_e32 v150, 1.0, v150
	v_add_f32_e32 v151, 1.0, v151
	v_rcp_f32_e32 v148, v148
	v_rcp_f32_e32 v149, v149
	v_rcp_f32_e32 v150, v150
	v_rcp_f32_e32 v151, v151
	s_nop 0
	v_pk_mul_f32 v[110:111], v[110:111], v[148:149]
	v_pk_mul_f32 v[112:113], v[112:113], v[150:151]
	v_pk_mul_f32 v[118:119], v[118:119], v[110:111]
	v_pk_mul_f32 v[120:121], v[120:121], v[112:113]
	v_cvt_pk_bf16_f32 v164, v114, v115
	v_cvt_pk_bf16_f32 v165, v116, v117
	v_cvt_pk_bf16_f32 v166, v118, v119
	v_cvt_pk_bf16_f32 v167, v120, v121
	s_nop 1
	v_permlane16_swap_b32 v164, v166
	v_permlane16_swap_b32 v165, v167
	s_nop 1
	global_store_dwordx4 v157, v[164:167], s[42:43]
	v_mul_f32_e32 v148, 0xbfb8aa3b, v122
	v_mul_f32_e32 v149, 0xbfb8aa3b, v123
	v_mul_f32_e32 v150, 0xbfb8aa3b, v124
	v_mul_f32_e32 v151, 0xbfb8aa3b, v125
	v_exp_f32_e32 v148, v148
	v_exp_f32_e32 v149, v149
	v_exp_f32_e32 v150, v150
	v_exp_f32_e32 v151, v151
	v_add_f32_e32 v148, 1.0, v148
	v_add_f32_e32 v149, 1.0, v149
	v_add_f32_e32 v150, 1.0, v150
	v_add_f32_e32 v151, 1.0, v151
	v_rcp_f32_e32 v148, v148
	v_rcp_f32_e32 v149, v149
	v_rcp_f32_e32 v150, v150
	v_rcp_f32_e32 v151, v151
	s_nop 0
	v_pk_mul_f32 v[122:123], v[122:123], v[148:149]
	v_pk_mul_f32 v[124:125], v[124:125], v[150:151]
	v_pk_mul_f32 v[136:137], v[136:137], v[122:123]
	v_pk_mul_f32 v[138:139], v[138:139], v[124:125]
	v_mul_f32_e32 v148, 0xbfb8aa3b, v126
	v_mul_f32_e32 v149, 0xbfb8aa3b, v127
	v_mul_f32_e32 v150, 0xbfb8aa3b, v128
	v_mul_f32_e32 v151, 0xbfb8aa3b, v129
	v_exp_f32_e32 v148, v148
	v_exp_f32_e32 v149, v149
	v_exp_f32_e32 v150, v150
	v_exp_f32_e32 v151, v151
	v_add_f32_e32 v148, 1.0, v148
	v_add_f32_e32 v149, 1.0, v149
	v_add_f32_e32 v150, 1.0, v150
	v_add_f32_e32 v151, 1.0, v151
	v_rcp_f32_e32 v148, v148
	v_rcp_f32_e32 v149, v149
	v_rcp_f32_e32 v150, v150
	v_rcp_f32_e32 v151, v151
	s_nop 0
	v_pk_mul_f32 v[126:127], v[126:127], v[148:149]
	v_pk_mul_f32 v[128:129], v[128:129], v[150:151]
	v_pk_mul_f32 v[140:141], v[140:141], v[126:127]
	v_pk_mul_f32 v[142:143], v[142:143], v[128:129]
	v_cvt_pk_bf16_f32 v168, v136, v137
	v_cvt_pk_bf16_f32 v169, v138, v139
	v_cvt_pk_bf16_f32 v170, v140, v141
	v_cvt_pk_bf16_f32 v171, v142, v143
	s_nop 1
	v_permlane16_swap_b32 v168, v170
	v_permlane16_swap_b32 v169, v171
	s_nop 1
	global_store_dwordx4 v157, v[168:171], s[42:43] offset:64
